# plus: 1/3 of deferred weight transposes moved into P1 tail slack (WG>=73), 4-stage transposer, layer-2 HC prefetch
# baseline (speedup 1.0000x reference)
.LBB0_325:
	s_cmp_lt_u32 s2, 73
	s_cbranch_scc1 .Lrc_p1skip
	s_mov_b64 exec, -1
	v_readlane_b32 s0, v254, 0
	v_readlane_b32 s1, v254, 1
	s_nop 4
	s_load_dwordx2 s[56:57], s[0:1], 0xa8
	s_load_dwordx2 s[58:59], s[0:1], 0xc0
	s_load_dwordx2 s[60:61], s[0:1], 0x88
	s_load_dwordx2 s[62:63], s[0:1], 0x78
	s_load_dwordx2 s[64:65], s[0:1], 0x80
	s_load_dwordx2 s[66:67], s[0:1], 0x90
	s_load_dwordx2 s[68:69], s[0:1], 0xa0
	s_load_dwordx2 s[70:71], s[0:1], 0x48
	s_load_dwordx2 s[72:73], s[0:1], 0xd8
	s_load_dword s3, s[0:1], 0xe8
	v_readfirstlane_b32 s4, v0
	v_and_b32_e32 v7, 63, v0
	s_lshr_b32 s4, s4, 6
	v_lshrrev_b32_e32 v1, 3, v7
	v_and_b32_e32 v2, 7, v7
	s_lshl_b32 s5, s4, 14
	v_lshlrev_b32_e32 v5, 5, v2
	s_movk_i32 s14, 0x420
	v_mul_u32_u24_e32 v4, s14, v2
	v_lshlrev_b32_e32 v2, 4, v2
	s_movk_i32 s14, 0x84
	v_mad_u32_u24 v3, v1, s14, v2
	v_lshl_add_u32 v4, v1, 2, v4
	v_add_u32_e32 v3, s5, v3
	v_add_u32_e32 v4, s5, v4
	v_mov_b32_e32 v207, v3
	v_add_u32_e32 v208, 1056, v3
	v_add_u32_e32 v209, 2112, v3
	v_add_u32_e32 v210, 3168, v3
	v_add_u32_e32 v211, 4224, v3
	v_add_u32_e32 v212, 5280, v3
	v_add_u32_e32 v213, 6336, v3
	v_add_u32_e32 v214, 7392, v3
	s_waitcnt lgkmcnt(0)
	s_sub_u32 s5, s2, 73
	s_lshl_b32 s5, s5, 3
	s_add_u32 s20, s5, s4
	s_sub_u32 s21, s3, 73
	s_lshl_b32 s21, s21, 3
	s_cmp_ge_u32 s20, 0x1c98
	s_cbranch_scc1 .Lrc_p1skip
	s_mov_b32 s42, 0
	s_mov_b32 s43, 0
	s_mov_b32 s26, s20
	s_cmp_lt_u32 s26, 0x2c00
	s_cbranch_scc1 .Ltrp1_i1_s0
	s_sub_u32 s26, s26, 0x2c00
	s_cmp_lt_u32 s26, 0x1600
	s_cbranch_scc1 .Ltrp1_i1_s1
	s_sub_u32 s26, s26, 0x1600
	s_cmp_lt_u32 s26, 0x800
	s_cbranch_scc1 .Ltrp1_i1_s2
	s_sub_u32 s26, s26, 0x800
	s_cmp_lt_u32 s26, 0x400
	s_cbranch_scc1 .Ltrp1_i1_s3
	s_sub_u32 s26, s26, 0x400
	s_cmp_lt_u32 s26, 0x400
	s_cbranch_scc1 .Ltrp1_i1_s4
	s_sub_u32 s26, s26, 0x400
	s_cmp_lt_u32 s26, 0x200
	s_cbranch_scc1 .Ltrp1_i1_s5
	s_sub_u32 s26, s26, 0x200
	s_branch .Ltrp1_i1_s6

.Ltrp1_i1_c:
	s_lshl_b32 s4, s24, 6
	s_mul_i32 s4, s25, s4
	s_lshl_b32 s5, s27, 7
	s_add_u32 s4, s4, s5
	s_add_u32 s10, s22, s4
	s_addc_u32 s11, s23, 0
	v_mad_u32_u24 v6, v1, s24, v2
	s_lshl_b32 s4, s29, 5
	s_mul_i32 s4, s27, s4
	s_lshl_b32 s5, s25, 7
	s_add_u32 s4, s4, s5
	s_add_u32 s4, s4, s28
	s_add_u32 s74, s72, s4
	s_addc_u32 s75, s73, 0
	s_mov_b32 s76, s29
	s_mov_b32 s77, s31
	s_lshl_b32 s4, s25, 8
	s_add_u32 s4, s4, s30
	s_add_u32 s12, s70, s4
	s_addc_u32 s13, s71, 0
	s_lshl_b32 s14, s24, 3
	global_load_dwordx4 v[44:47], v6, s[10:11]
	s_add_u32 s10, s10, s14
	s_addc_u32 s11, s11, 0
	global_load_dwordx4 v[48:51], v6, s[10:11]
	s_add_u32 s10, s10, s14
	s_addc_u32 s11, s11, 0
	global_load_dwordx4 v[52:55], v6, s[10:11]
	s_add_u32 s10, s10, s14
	s_addc_u32 s11, s11, 0
	global_load_dwordx4 v[56:59], v6, s[10:11]
	s_add_u32 s10, s10, s14
	s_addc_u32 s11, s11, 0
	global_load_dwordx4 v[60:63], v6, s[10:11]
	s_add_u32 s10, s10, s14
	s_addc_u32 s11, s11, 0
	global_load_dwordx4 v[64:67], v6, s[10:11]
	s_add_u32 s10, s10, s14
	s_addc_u32 s11, s11, 0
	global_load_dwordx4 v[68:71], v6, s[10:11]
	s_add_u32 s10, s10, s14
	s_addc_u32 s11, s11, 0
	global_load_dwordx4 v[72:75], v6, s[10:11]
	global_load_dwordx4 v[76:79], v5, s[12:13]
	global_load_dwordx4 v[80:83], v5, s[12:13] offset:16
	s_add_u32 s20, s20, s21
	s_add_u32 s42, s42, 1
	s_cmp_ge_u32 s20, 0x1c98
	s_cbranch_scc1 .Ltrp1_st0
	s_mov_b32 s26, s20
	s_cmp_lt_u32 s26, 0x2c00
	s_cbranch_scc1 .Ltrp1_i2_s0
	s_sub_u32 s26, s26, 0x2c00
	s_cmp_lt_u32 s26, 0x1600
	s_cbranch_scc1 .Ltrp1_i2_s1
	s_sub_u32 s26, s26, 0x1600
	s_cmp_lt_u32 s26, 0x800
	s_cbranch_scc1 .Ltrp1_i2_s2
	s_sub_u32 s26, s26, 0x800
	s_cmp_lt_u32 s26, 0x400
	s_cbranch_scc1 .Ltrp1_i2_s3
	s_sub_u32 s26, s26, 0x400
	s_cmp_lt_u32 s26, 0x400
	s_cbranch_scc1 .Ltrp1_i2_s4
	s_sub_u32 s26, s26, 0x400
	s_cmp_lt_u32 s26, 0x200
	s_cbranch_scc1 .Ltrp1_i2_s5
	s_sub_u32 s26, s26, 0x200
	s_branch .Ltrp1_i2_s6

.Ltrp1_i2_c:
	s_lshl_b32 s4, s24, 6
	s_mul_i32 s4, s25, s4
	s_lshl_b32 s5, s27, 7
	s_add_u32 s4, s4, s5
	s_add_u32 s10, s22, s4
	s_addc_u32 s11, s23, 0
	v_mad_u32_u24 v6, v1, s24, v2
	s_lshl_b32 s4, s29, 5
	s_mul_i32 s4, s27, s4
	s_lshl_b32 s5, s25, 7
	s_add_u32 s4, s4, s5
	s_add_u32 s4, s4, s28
	s_add_u32 s78, s72, s4
	s_addc_u32 s79, s73, 0
	s_mov_b32 s80, s29
	s_mov_b32 s81, s31
	s_lshl_b32 s4, s25, 8
	s_add_u32 s4, s4, s30
	s_add_u32 s12, s70, s4
	s_addc_u32 s13, s71, 0
	s_lshl_b32 s14, s24, 3
	global_load_dwordx4 v[84:87], v6, s[10:11]
	s_add_u32 s10, s10, s14
	s_addc_u32 s11, s11, 0
	global_load_dwordx4 v[88:91], v6, s[10:11]
	s_add_u32 s10, s10, s14
	s_addc_u32 s11, s11, 0
	global_load_dwordx4 v[92:95], v6, s[10:11]
	s_add_u32 s10, s10, s14
	s_addc_u32 s11, s11, 0
	global_load_dwordx4 v[96:99], v6, s[10:11]
	s_add_u32 s10, s10, s14
	s_addc_u32 s11, s11, 0
	global_load_dwordx4 v[100:103], v6, s[10:11]
	s_add_u32 s10, s10, s14
	s_addc_u32 s11, s11, 0
	global_load_dwordx4 v[104:107], v6, s[10:11]
	s_add_u32 s10, s10, s14
	s_addc_u32 s11, s11, 0
	global_load_dwordx4 v[108:111], v6, s[10:11]
	s_add_u32 s10, s10, s14
	s_addc_u32 s11, s11, 0
	global_load_dwordx4 v[112:115], v6, s[10:11]
	global_load_dwordx4 v[116:119], v5, s[12:13]
	global_load_dwordx4 v[120:123], v5, s[12:13] offset:16
	s_add_u32 s20, s20, s21
	s_add_u32 s42, s42, 1
	s_cmp_ge_u32 s20, 0x1c98
	s_cbranch_scc1 .Ltrp1_st0
	s_mov_b32 s26, s20
	s_cmp_lt_u32 s26, 0x2c00
	s_cbranch_scc1 .Ltrp1_i3_s0
	s_sub_u32 s26, s26, 0x2c00
	s_cmp_lt_u32 s26, 0x1600
	s_cbranch_scc1 .Ltrp1_i3_s1
	s_sub_u32 s26, s26, 0x1600
	s_cmp_lt_u32 s26, 0x800
	s_cbranch_scc1 .Ltrp1_i3_s2
	s_sub_u32 s26, s26, 0x800
	s_cmp_lt_u32 s26, 0x400
	s_cbranch_scc1 .Ltrp1_i3_s3
	s_sub_u32 s26, s26, 0x400
	s_cmp_lt_u32 s26, 0x400
	s_cbranch_scc1 .Ltrp1_i3_s4
	s_sub_u32 s26, s26, 0x400
	s_cmp_lt_u32 s26, 0x200
	s_cbranch_scc1 .Ltrp1_i3_s5
	s_sub_u32 s26, s26, 0x200
	s_branch .Ltrp1_i3_s6

.Ltrp1_i3_c:
	s_lshl_b32 s4, s24, 6
	s_mul_i32 s4, s25, s4
	s_lshl_b32 s5, s27, 7
	s_add_u32 s4, s4, s5
	s_add_u32 s10, s22, s4
	s_addc_u32 s11, s23, 0
	v_mad_u32_u24 v6, v1, s24, v2
	s_lshl_b32 s4, s29, 5
	s_mul_i32 s4, s27, s4
	s_lshl_b32 s5, s25, 7
	s_add_u32 s4, s4, s5
	s_add_u32 s4, s4, s28
	s_add_u32 s82, s72, s4
	s_addc_u32 s83, s73, 0
	s_mov_b32 s84, s29
	s_mov_b32 s85, s31
	s_lshl_b32 s4, s25, 8
	s_add_u32 s4, s4, s30
	s_add_u32 s12, s70, s4
	s_addc_u32 s13, s71, 0
	s_lshl_b32 s14, s24, 3
	global_load_dwordx4 v[124:127], v6, s[10:11]
	s_add_u32 s10, s10, s14
	s_addc_u32 s11, s11, 0
	global_load_dwordx4 v[128:131], v6, s[10:11]
	s_add_u32 s10, s10, s14
	s_addc_u32 s11, s11, 0
	global_load_dwordx4 v[132:135], v6, s[10:11]
	s_add_u32 s10, s10, s14
	s_addc_u32 s11, s11, 0
	global_load_dwordx4 v[136:139], v6, s[10:11]
	s_add_u32 s10, s10, s14
	s_addc_u32 s11, s11, 0
	global_load_dwordx4 v[140:143], v6, s[10:11]
	s_add_u32 s10, s10, s14
	s_addc_u32 s11, s11, 0
	global_load_dwordx4 v[144:147], v6, s[10:11]
	s_add_u32 s10, s10, s14
	s_addc_u32 s11, s11, 0
	global_load_dwordx4 v[148:151], v6, s[10:11]
	s_add_u32 s10, s10, s14
	s_addc_u32 s11, s11, 0
	global_load_dwordx4 v[152:155], v6, s[10:11]
	global_load_dwordx4 v[156:159], v5, s[12:13]
	global_load_dwordx4 v[160:163], v5, s[12:13] offset:16
	s_add_u32 s20, s20, s21
	s_add_u32 s42, s42, 1
	s_cmp_ge_u32 s20, 0x1c98
	s_cbranch_scc1 .Ltrp1_st0
	s_mov_b32 s26, s20
	s_cmp_lt_u32 s26, 0x2c00
	s_cbranch_scc1 .Ltrp1_i4_s0
	s_sub_u32 s26, s26, 0x2c00
	s_cmp_lt_u32 s26, 0x1600
	s_cbranch_scc1 .Ltrp1_i4_s1
	s_sub_u32 s26, s26, 0x1600
	s_cmp_lt_u32 s26, 0x800
	s_cbranch_scc1 .Ltrp1_i4_s2
	s_sub_u32 s26, s26, 0x800
	s_cmp_lt_u32 s26, 0x400
	s_cbranch_scc1 .Ltrp1_i4_s3
	s_sub_u32 s26, s26, 0x400
	s_cmp_lt_u32 s26, 0x400
	s_cbranch_scc1 .Ltrp1_i4_s4
	s_sub_u32 s26, s26, 0x400
	s_cmp_lt_u32 s26, 0x200
	s_cbranch_scc1 .Ltrp1_i4_s5
	s_sub_u32 s26, s26, 0x200
	s_branch .Ltrp1_i4_s6

.Ltrp1_i4_c:
	s_lshl_b32 s4, s24, 6
	s_mul_i32 s4, s25, s4
	s_lshl_b32 s5, s27, 7
	s_add_u32 s4, s4, s5
	s_add_u32 s10, s22, s4
	s_addc_u32 s11, s23, 0
	v_mad_u32_u24 v6, v1, s24, v2
	s_lshl_b32 s4, s29, 5
	s_mul_i32 s4, s27, s4
	s_lshl_b32 s5, s25, 7
	s_add_u32 s4, s4, s5
	s_add_u32 s4, s4, s28
	s_add_u32 s86, s72, s4
	s_addc_u32 s87, s73, 0
	s_mov_b32 s88, s29
	s_mov_b32 s90, s31
	s_lshl_b32 s4, s25, 8
	s_add_u32 s4, s4, s30
	s_add_u32 s12, s70, s4
	s_addc_u32 s13, s71, 0
	s_lshl_b32 s14, s24, 3
	global_load_dwordx4 v[164:167], v6, s[10:11]
	s_add_u32 s10, s10, s14
	s_addc_u32 s11, s11, 0
	global_load_dwordx4 v[168:171], v6, s[10:11]
	s_add_u32 s10, s10, s14
	s_addc_u32 s11, s11, 0
	global_load_dwordx4 v[172:175], v6, s[10:11]
	s_add_u32 s10, s10, s14
	s_addc_u32 s11, s11, 0
	global_load_dwordx4 v[176:179], v6, s[10:11]
	s_add_u32 s10, s10, s14
	s_addc_u32 s11, s11, 0
	global_load_dwordx4 v[180:183], v6, s[10:11]
	s_add_u32 s10, s10, s14
	s_addc_u32 s11, s11, 0
	global_load_dwordx4 v[184:187], v6, s[10:11]
	s_add_u32 s10, s10, s14
	s_addc_u32 s11, s11, 0
	global_load_dwordx4 v[188:191], v6, s[10:11]
	s_add_u32 s10, s10, s14
	s_addc_u32 s11, s11, 0
	global_load_dwordx4 v[192:195], v6, s[10:11]
	global_load_dwordx4 v[196:199], v5, s[12:13]
	global_load_dwordx4 v[200:203], v5, s[12:13] offset:16
	s_add_u32 s20, s20, s21
	s_add_u32 s42, s42, 1
.Ltrp1_st0:
	s_cmp_lg_u32 s42, 4
	s_cbranch_scc1 .Ltrp1_w0_0
	s_cmp_lt_u32 s43, 4
	s_cbranch_scc1 .Ltrp1_w1_0
	s_waitcnt vmcnt(42)
	s_branch .Ltrp1_go_0
.Ltrp1_w1_0:
	s_waitcnt vmcnt(30)
	s_branch .Ltrp1_go_0

.Ltrp1_go_0:
	ds_write2_b32 v207, v44, v45 offset1:1
	ds_write2_b32 v207, v46, v47 offset0:2 offset1:3
	ds_write2_b32 v208, v48, v49 offset1:1
	ds_write2_b32 v208, v50, v51 offset0:2 offset1:3
	ds_write2_b32 v209, v52, v53 offset1:1
	ds_write2_b32 v209, v54, v55 offset0:2 offset1:3
	ds_write2_b32 v210, v56, v57 offset1:1
	ds_write2_b32 v210, v58, v59 offset0:2 offset1:3
	ds_write2_b32 v211, v60, v61 offset1:1
	ds_write2_b32 v211, v62, v63 offset0:2 offset1:3
	ds_write2_b32 v212, v64, v65 offset1:1
	ds_write2_b32 v212, v66, v67 offset0:2 offset1:3
	ds_write2_b32 v213, v68, v69 offset1:1
	ds_write2_b32 v213, v70, v71 offset0:2 offset1:3
	ds_write2_b32 v214, v72, v73 offset1:1
	ds_write2_b32 v214, v74, v75 offset0:2 offset1:3
	v_mad_u32_u24 v8, v1, s76, v2
	s_lshl_b32 s4, s76, 3
	s_nop 0
	v_add_u32_e32 v9, s4, v8
	v_add_u32_e32 v10, s4, v9
	v_add_u32_e32 v11, s4, v10
	s_waitcnt lgkmcnt(0)
	ds_read2_b32 v[12:13], v4 offset1:33
	ds_read2_b32 v[14:15], v4 offset0:66 offset1:99
	ds_read2_b32 v[16:17], v4 offset0:132 offset1:165
	ds_read2_b32 v[18:19], v4 offset0:198 offset1:231
	ds_read2_b32 v[20:21], v4 offset0:8 offset1:41
	ds_read2_b32 v[22:23], v4 offset0:74 offset1:107
	ds_read2_b32 v[24:25], v4 offset0:140 offset1:173
	ds_read2_b32 v[26:27], v4 offset0:206 offset1:239
	ds_read2_b32 v[28:29], v4 offset0:16 offset1:49
	ds_read2_b32 v[30:31], v4 offset0:82 offset1:115
	ds_read2_b32 v[32:33], v4 offset0:148 offset1:181
	ds_read2_b32 v[34:35], v4 offset0:214 offset1:247
	ds_read2_b32 v[36:37], v4 offset0:24 offset1:57
	ds_read2_b32 v[38:39], v4 offset0:90 offset1:123
	ds_read2_b32 v[40:41], v4 offset0:156 offset1:189
	ds_read2_b32 v[42:43], v4 offset0:222 offset1:255
	s_cmp_eq_u32 s77, 0
	s_waitcnt lgkmcnt(0)
	s_cbranch_scc1 .Ltrp1_p5_ng
	v_mul_f32_e32 v12, v76, v12
	v_mul_f32_e32 v13, v77, v13
	v_mul_f32_e32 v14, v78, v14
	v_mul_f32_e32 v15, v79, v15
	v_mul_f32_e32 v16, v80, v16
	v_mul_f32_e32 v17, v81, v17
	v_mul_f32_e32 v18, v82, v18
	v_mul_f32_e32 v19, v83, v19
	v_mul_f32_e32 v20, v76, v20
	v_mul_f32_e32 v21, v77, v21
	v_mul_f32_e32 v22, v78, v22
	v_mul_f32_e32 v23, v79, v23
	v_mul_f32_e32 v24, v80, v24
	v_mul_f32_e32 v25, v81, v25
	v_mul_f32_e32 v26, v82, v26
	v_mul_f32_e32 v27, v83, v27
	v_mul_f32_e32 v28, v76, v28
	v_mul_f32_e32 v29, v77, v29
	v_mul_f32_e32 v30, v78, v30
	v_mul_f32_e32 v31, v79, v31
	v_mul_f32_e32 v32, v80, v32
	v_mul_f32_e32 v33, v81, v33
	v_mul_f32_e32 v34, v82, v34
	v_mul_f32_e32 v35, v83, v35
	v_mul_f32_e32 v36, v76, v36
	v_mul_f32_e32 v37, v77, v37
	v_mul_f32_e32 v38, v78, v38
	v_mul_f32_e32 v39, v79, v39
	v_mul_f32_e32 v40, v80, v40
	v_mul_f32_e32 v41, v81, v41
	v_mul_f32_e32 v42, v82, v42
	v_mul_f32_e32 v43, v83, v43
.Ltrp1_p5_ng:
	v_cvt_pk_bf16_f32 v12, v12, v13
	v_cvt_pk_bf16_f32 v13, v14, v15
	v_cvt_pk_bf16_f32 v14, v16, v17
	v_cvt_pk_bf16_f32 v15, v18, v19
	v_cvt_pk_bf16_f32 v20, v20, v21
	v_cvt_pk_bf16_f32 v21, v22, v23
	v_cvt_pk_bf16_f32 v22, v24, v25
	v_cvt_pk_bf16_f32 v23, v26, v27
	v_cvt_pk_bf16_f32 v28, v28, v29
	v_cvt_pk_bf16_f32 v29, v30, v31
	v_cvt_pk_bf16_f32 v30, v32, v33
	v_cvt_pk_bf16_f32 v31, v34, v35
	v_cvt_pk_bf16_f32 v36, v36, v37
	v_cvt_pk_bf16_f32 v37, v38, v39
	v_cvt_pk_bf16_f32 v38, v40, v41
	v_cvt_pk_bf16_f32 v39, v42, v43
	global_store_dwordx4 v8, v[12:15], s[74:75]
	global_store_dwordx4 v9, v[20:23], s[74:75]
	global_store_dwordx4 v10, v[28:31], s[74:75]
	global_store_dwordx4 v11, v[36:39], s[74:75]
	s_sub_u32 s42, s42, 1
	s_add_u32 s43, s43, 1
	s_cmp_ge_u32 s20, 0x1c98
	s_cbranch_scc1 .Ltrp1_ni_0
	s_mov_b32 s26, s20
	s_cmp_lt_u32 s26, 0x2c00
	s_cbranch_scc1 .Ltrp1_i6_s0
	s_sub_u32 s26, s26, 0x2c00
	s_cmp_lt_u32 s26, 0x1600
	s_cbranch_scc1 .Ltrp1_i6_s1
	s_sub_u32 s26, s26, 0x1600
	s_cmp_lt_u32 s26, 0x800
	s_cbranch_scc1 .Ltrp1_i6_s2
	s_sub_u32 s26, s26, 0x800
	s_cmp_lt_u32 s26, 0x400
	s_cbranch_scc1 .Ltrp1_i6_s3
	s_sub_u32 s26, s26, 0x400
	s_cmp_lt_u32 s26, 0x400
	s_cbranch_scc1 .Ltrp1_i6_s4
	s_sub_u32 s26, s26, 0x400
	s_cmp_lt_u32 s26, 0x200
	s_cbranch_scc1 .Ltrp1_i6_s5
	s_sub_u32 s26, s26, 0x200
	s_branch .Ltrp1_i6_s6

.Ltrp1_i6_c:
	s_lshl_b32 s4, s24, 6
	s_mul_i32 s4, s25, s4
	s_lshl_b32 s5, s27, 7
	s_add_u32 s4, s4, s5
	s_add_u32 s10, s22, s4
	s_addc_u32 s11, s23, 0
	v_mad_u32_u24 v6, v1, s24, v2
	s_lshl_b32 s4, s29, 5
	s_mul_i32 s4, s27, s4
	s_lshl_b32 s5, s25, 7
	s_add_u32 s4, s4, s5
	s_add_u32 s4, s4, s28
	s_add_u32 s74, s72, s4
	s_addc_u32 s75, s73, 0
	s_mov_b32 s76, s29
	s_mov_b32 s77, s31
	s_lshl_b32 s4, s25, 8
	s_add_u32 s4, s4, s30
	s_add_u32 s12, s70, s4
	s_addc_u32 s13, s71, 0
	s_lshl_b32 s14, s24, 3
	global_load_dwordx4 v[44:47], v6, s[10:11]
	s_add_u32 s10, s10, s14
	s_addc_u32 s11, s11, 0
	global_load_dwordx4 v[48:51], v6, s[10:11]
	s_add_u32 s10, s10, s14
	s_addc_u32 s11, s11, 0
	global_load_dwordx4 v[52:55], v6, s[10:11]
	s_add_u32 s10, s10, s14
	s_addc_u32 s11, s11, 0
	global_load_dwordx4 v[56:59], v6, s[10:11]
	s_add_u32 s10, s10, s14
	s_addc_u32 s11, s11, 0
	global_load_dwordx4 v[60:63], v6, s[10:11]
	s_add_u32 s10, s10, s14
	s_addc_u32 s11, s11, 0
	global_load_dwordx4 v[64:67], v6, s[10:11]
	s_add_u32 s10, s10, s14
	s_addc_u32 s11, s11, 0
	global_load_dwordx4 v[68:71], v6, s[10:11]
	s_add_u32 s10, s10, s14
	s_addc_u32 s11, s11, 0
	global_load_dwordx4 v[72:75], v6, s[10:11]
	global_load_dwordx4 v[76:79], v5, s[12:13]
	global_load_dwordx4 v[80:83], v5, s[12:13] offset:16
	s_add_u32 s20, s20, s21
	s_add_u32 s42, s42, 1

.Ltrp1_go_1:
	ds_write2_b32 v207, v84, v85 offset1:1
	ds_write2_b32 v207, v86, v87 offset0:2 offset1:3
	ds_write2_b32 v208, v88, v89 offset1:1
	ds_write2_b32 v208, v90, v91 offset0:2 offset1:3
	ds_write2_b32 v209, v92, v93 offset1:1
	ds_write2_b32 v209, v94, v95 offset0:2 offset1:3
	ds_write2_b32 v210, v96, v97 offset1:1
	ds_write2_b32 v210, v98, v99 offset0:2 offset1:3
	ds_write2_b32 v211, v100, v101 offset1:1
	ds_write2_b32 v211, v102, v103 offset0:2 offset1:3
	ds_write2_b32 v212, v104, v105 offset1:1
	ds_write2_b32 v212, v106, v107 offset0:2 offset1:3
	ds_write2_b32 v213, v108, v109 offset1:1
	ds_write2_b32 v213, v110, v111 offset0:2 offset1:3
	ds_write2_b32 v214, v112, v113 offset1:1
	ds_write2_b32 v214, v114, v115 offset0:2 offset1:3
	v_mad_u32_u24 v8, v1, s80, v2
	s_lshl_b32 s4, s80, 3
	s_nop 0
	v_add_u32_e32 v9, s4, v8
	v_add_u32_e32 v10, s4, v9
	v_add_u32_e32 v11, s4, v10
	s_waitcnt lgkmcnt(0)
	ds_read2_b32 v[12:13], v4 offset1:33
	ds_read2_b32 v[14:15], v4 offset0:66 offset1:99
	ds_read2_b32 v[16:17], v4 offset0:132 offset1:165
	ds_read2_b32 v[18:19], v4 offset0:198 offset1:231
	ds_read2_b32 v[20:21], v4 offset0:8 offset1:41
	ds_read2_b32 v[22:23], v4 offset0:74 offset1:107
	ds_read2_b32 v[24:25], v4 offset0:140 offset1:173
	ds_read2_b32 v[26:27], v4 offset0:206 offset1:239
	ds_read2_b32 v[28:29], v4 offset0:16 offset1:49
	ds_read2_b32 v[30:31], v4 offset0:82 offset1:115
	ds_read2_b32 v[32:33], v4 offset0:148 offset1:181
	ds_read2_b32 v[34:35], v4 offset0:214 offset1:247
	ds_read2_b32 v[36:37], v4 offset0:24 offset1:57
	ds_read2_b32 v[38:39], v4 offset0:90 offset1:123
	ds_read2_b32 v[40:41], v4 offset0:156 offset1:189
	ds_read2_b32 v[42:43], v4 offset0:222 offset1:255
	s_cmp_eq_u32 s81, 0
	s_waitcnt lgkmcnt(0)
	s_cbranch_scc1 .Ltrp1_p7_ng
	v_mul_f32_e32 v12, v116, v12
	v_mul_f32_e32 v13, v117, v13
	v_mul_f32_e32 v14, v118, v14
	v_mul_f32_e32 v15, v119, v15
	v_mul_f32_e32 v16, v120, v16
	v_mul_f32_e32 v17, v121, v17
	v_mul_f32_e32 v18, v122, v18
	v_mul_f32_e32 v19, v123, v19
	v_mul_f32_e32 v20, v116, v20
	v_mul_f32_e32 v21, v117, v21
	v_mul_f32_e32 v22, v118, v22
	v_mul_f32_e32 v23, v119, v23
	v_mul_f32_e32 v24, v120, v24
	v_mul_f32_e32 v25, v121, v25
	v_mul_f32_e32 v26, v122, v26
	v_mul_f32_e32 v27, v123, v27
	v_mul_f32_e32 v28, v116, v28
	v_mul_f32_e32 v29, v117, v29
	v_mul_f32_e32 v30, v118, v30
	v_mul_f32_e32 v31, v119, v31
	v_mul_f32_e32 v32, v120, v32
	v_mul_f32_e32 v33, v121, v33
	v_mul_f32_e32 v34, v122, v34
	v_mul_f32_e32 v35, v123, v35
	v_mul_f32_e32 v36, v116, v36
	v_mul_f32_e32 v37, v117, v37
	v_mul_f32_e32 v38, v118, v38
	v_mul_f32_e32 v39, v119, v39
	v_mul_f32_e32 v40, v120, v40
	v_mul_f32_e32 v41, v121, v41
	v_mul_f32_e32 v42, v122, v42
	v_mul_f32_e32 v43, v123, v43
.Ltrp1_p7_ng:
	v_cvt_pk_bf16_f32 v12, v12, v13
	v_cvt_pk_bf16_f32 v13, v14, v15
	v_cvt_pk_bf16_f32 v14, v16, v17
	v_cvt_pk_bf16_f32 v15, v18, v19
	v_cvt_pk_bf16_f32 v20, v20, v21
	v_cvt_pk_bf16_f32 v21, v22, v23
	v_cvt_pk_bf16_f32 v22, v24, v25
	v_cvt_pk_bf16_f32 v23, v26, v27
	v_cvt_pk_bf16_f32 v28, v28, v29
	v_cvt_pk_bf16_f32 v29, v30, v31
	v_cvt_pk_bf16_f32 v30, v32, v33
	v_cvt_pk_bf16_f32 v31, v34, v35
	v_cvt_pk_bf16_f32 v36, v36, v37
	v_cvt_pk_bf16_f32 v37, v38, v39
	v_cvt_pk_bf16_f32 v38, v40, v41
	v_cvt_pk_bf16_f32 v39, v42, v43
	global_store_dwordx4 v8, v[12:15], s[78:79]
	global_store_dwordx4 v9, v[20:23], s[78:79]
	global_store_dwordx4 v10, v[28:31], s[78:79]
	global_store_dwordx4 v11, v[36:39], s[78:79]
	s_sub_u32 s42, s42, 1
	s_add_u32 s43, s43, 1
	s_cmp_ge_u32 s20, 0x1c98
	s_cbranch_scc1 .Ltrp1_ni_1
	s_mov_b32 s26, s20
	s_cmp_lt_u32 s26, 0x2c00
	s_cbranch_scc1 .Ltrp1_i8_s0
	s_sub_u32 s26, s26, 0x2c00
	s_cmp_lt_u32 s26, 0x1600
	s_cbranch_scc1 .Ltrp1_i8_s1
	s_sub_u32 s26, s26, 0x1600
	s_cmp_lt_u32 s26, 0x800
	s_cbranch_scc1 .Ltrp1_i8_s2
	s_sub_u32 s26, s26, 0x800
	s_cmp_lt_u32 s26, 0x400
	s_cbranch_scc1 .Ltrp1_i8_s3
	s_sub_u32 s26, s26, 0x400
	s_cmp_lt_u32 s26, 0x400
	s_cbranch_scc1 .Ltrp1_i8_s4
	s_sub_u32 s26, s26, 0x400
	s_cmp_lt_u32 s26, 0x200
	s_cbranch_scc1 .Ltrp1_i8_s5
	s_sub_u32 s26, s26, 0x200
	s_branch .Ltrp1_i8_s6

.Ltrp1_i8_c:
	s_lshl_b32 s4, s24, 6
	s_mul_i32 s4, s25, s4
	s_lshl_b32 s5, s27, 7
	s_add_u32 s4, s4, s5
	s_add_u32 s10, s22, s4
	s_addc_u32 s11, s23, 0
	v_mad_u32_u24 v6, v1, s24, v2
	s_lshl_b32 s4, s29, 5
	s_mul_i32 s4, s27, s4
	s_lshl_b32 s5, s25, 7
	s_add_u32 s4, s4, s5
	s_add_u32 s4, s4, s28
	s_add_u32 s78, s72, s4
	s_addc_u32 s79, s73, 0
	s_mov_b32 s80, s29
	s_mov_b32 s81, s31
	s_lshl_b32 s4, s25, 8
	s_add_u32 s4, s4, s30
	s_add_u32 s12, s70, s4
	s_addc_u32 s13, s71, 0
	s_lshl_b32 s14, s24, 3
	global_load_dwordx4 v[84:87], v6, s[10:11]
	s_add_u32 s10, s10, s14
	s_addc_u32 s11, s11, 0
	global_load_dwordx4 v[88:91], v6, s[10:11]
	s_add_u32 s10, s10, s14
	s_addc_u32 s11, s11, 0
	global_load_dwordx4 v[92:95], v6, s[10:11]
	s_add_u32 s10, s10, s14
	s_addc_u32 s11, s11, 0
	global_load_dwordx4 v[96:99], v6, s[10:11]
	s_add_u32 s10, s10, s14
	s_addc_u32 s11, s11, 0
	global_load_dwordx4 v[100:103], v6, s[10:11]
	s_add_u32 s10, s10, s14
	s_addc_u32 s11, s11, 0
	global_load_dwordx4 v[104:107], v6, s[10:11]
	s_add_u32 s10, s10, s14
	s_addc_u32 s11, s11, 0
	global_load_dwordx4 v[108:111], v6, s[10:11]
	s_add_u32 s10, s10, s14
	s_addc_u32 s11, s11, 0
	global_load_dwordx4 v[112:115], v6, s[10:11]
	global_load_dwordx4 v[116:119], v5, s[12:13]
	global_load_dwordx4 v[120:123], v5, s[12:13] offset:16
	s_add_u32 s20, s20, s21
	s_add_u32 s42, s42, 1

.Ltrp1_go_2:
	ds_write2_b32 v207, v124, v125 offset1:1
	ds_write2_b32 v207, v126, v127 offset0:2 offset1:3
	ds_write2_b32 v208, v128, v129 offset1:1
	ds_write2_b32 v208, v130, v131 offset0:2 offset1:3
	ds_write2_b32 v209, v132, v133 offset1:1
	ds_write2_b32 v209, v134, v135 offset0:2 offset1:3
	ds_write2_b32 v210, v136, v137 offset1:1
	ds_write2_b32 v210, v138, v139 offset0:2 offset1:3
	ds_write2_b32 v211, v140, v141 offset1:1
	ds_write2_b32 v211, v142, v143 offset0:2 offset1:3
	ds_write2_b32 v212, v144, v145 offset1:1
	ds_write2_b32 v212, v146, v147 offset0:2 offset1:3
	ds_write2_b32 v213, v148, v149 offset1:1
	ds_write2_b32 v213, v150, v151 offset0:2 offset1:3
	ds_write2_b32 v214, v152, v153 offset1:1
	ds_write2_b32 v214, v154, v155 offset0:2 offset1:3
	v_mad_u32_u24 v8, v1, s84, v2
	s_lshl_b32 s4, s84, 3
	s_nop 0
	v_add_u32_e32 v9, s4, v8
	v_add_u32_e32 v10, s4, v9
	v_add_u32_e32 v11, s4, v10
	s_waitcnt lgkmcnt(0)
	ds_read2_b32 v[12:13], v4 offset1:33
	ds_read2_b32 v[14:15], v4 offset0:66 offset1:99
	ds_read2_b32 v[16:17], v4 offset0:132 offset1:165
	ds_read2_b32 v[18:19], v4 offset0:198 offset1:231
	ds_read2_b32 v[20:21], v4 offset0:8 offset1:41
	ds_read2_b32 v[22:23], v4 offset0:74 offset1:107
	ds_read2_b32 v[24:25], v4 offset0:140 offset1:173
	ds_read2_b32 v[26:27], v4 offset0:206 offset1:239
	ds_read2_b32 v[28:29], v4 offset0:16 offset1:49
	ds_read2_b32 v[30:31], v4 offset0:82 offset1:115
	ds_read2_b32 v[32:33], v4 offset0:148 offset1:181
	ds_read2_b32 v[34:35], v4 offset0:214 offset1:247
	ds_read2_b32 v[36:37], v4 offset0:24 offset1:57
	ds_read2_b32 v[38:39], v4 offset0:90 offset1:123
	ds_read2_b32 v[40:41], v4 offset0:156 offset1:189
	ds_read2_b32 v[42:43], v4 offset0:222 offset1:255
	s_cmp_eq_u32 s85, 0
	s_waitcnt lgkmcnt(0)
	s_cbranch_scc1 .Ltrp1_p9_ng
	v_mul_f32_e32 v12, v156, v12
	v_mul_f32_e32 v13, v157, v13
	v_mul_f32_e32 v14, v158, v14
	v_mul_f32_e32 v15, v159, v15
	v_mul_f32_e32 v16, v160, v16
	v_mul_f32_e32 v17, v161, v17
	v_mul_f32_e32 v18, v162, v18
	v_mul_f32_e32 v19, v163, v19
	v_mul_f32_e32 v20, v156, v20
	v_mul_f32_e32 v21, v157, v21
	v_mul_f32_e32 v22, v158, v22
	v_mul_f32_e32 v23, v159, v23
	v_mul_f32_e32 v24, v160, v24
	v_mul_f32_e32 v25, v161, v25
	v_mul_f32_e32 v26, v162, v26
	v_mul_f32_e32 v27, v163, v27
	v_mul_f32_e32 v28, v156, v28
	v_mul_f32_e32 v29, v157, v29
	v_mul_f32_e32 v30, v158, v30
	v_mul_f32_e32 v31, v159, v31
	v_mul_f32_e32 v32, v160, v32
	v_mul_f32_e32 v33, v161, v33
	v_mul_f32_e32 v34, v162, v34
	v_mul_f32_e32 v35, v163, v35
	v_mul_f32_e32 v36, v156, v36
	v_mul_f32_e32 v37, v157, v37
	v_mul_f32_e32 v38, v158, v38
	v_mul_f32_e32 v39, v159, v39
	v_mul_f32_e32 v40, v160, v40
	v_mul_f32_e32 v41, v161, v41
	v_mul_f32_e32 v42, v162, v42
	v_mul_f32_e32 v43, v163, v43
.Ltrp1_p9_ng:
	v_cvt_pk_bf16_f32 v12, v12, v13
	v_cvt_pk_bf16_f32 v13, v14, v15
	v_cvt_pk_bf16_f32 v14, v16, v17
	v_cvt_pk_bf16_f32 v15, v18, v19
	v_cvt_pk_bf16_f32 v20, v20, v21
	v_cvt_pk_bf16_f32 v21, v22, v23
	v_cvt_pk_bf16_f32 v22, v24, v25
	v_cvt_pk_bf16_f32 v23, v26, v27
	v_cvt_pk_bf16_f32 v28, v28, v29
	v_cvt_pk_bf16_f32 v29, v30, v31
	v_cvt_pk_bf16_f32 v30, v32, v33
	v_cvt_pk_bf16_f32 v31, v34, v35
	v_cvt_pk_bf16_f32 v36, v36, v37
	v_cvt_pk_bf16_f32 v37, v38, v39
	v_cvt_pk_bf16_f32 v38, v40, v41
	v_cvt_pk_bf16_f32 v39, v42, v43
	global_store_dwordx4 v8, v[12:15], s[82:83]
	global_store_dwordx4 v9, v[20:23], s[82:83]
	global_store_dwordx4 v10, v[28:31], s[82:83]
	global_store_dwordx4 v11, v[36:39], s[82:83]
	s_sub_u32 s42, s42, 1
	s_add_u32 s43, s43, 1
	s_cmp_ge_u32 s20, 0x1c98
	s_cbranch_scc1 .Ltrp1_ni_2
	s_mov_b32 s26, s20
	s_cmp_lt_u32 s26, 0x2c00
	s_cbranch_scc1 .Ltrp1_i10_s0
	s_sub_u32 s26, s26, 0x2c00
	s_cmp_lt_u32 s26, 0x1600
	s_cbranch_scc1 .Ltrp1_i10_s1
	s_sub_u32 s26, s26, 0x1600
	s_cmp_lt_u32 s26, 0x800
	s_cbranch_scc1 .Ltrp1_i10_s2
	s_sub_u32 s26, s26, 0x800
	s_cmp_lt_u32 s26, 0x400
	s_cbranch_scc1 .Ltrp1_i10_s3
	s_sub_u32 s26, s26, 0x400
	s_cmp_lt_u32 s26, 0x400
	s_cbranch_scc1 .Ltrp1_i10_s4
	s_sub_u32 s26, s26, 0x400
	s_cmp_lt_u32 s26, 0x200
	s_cbranch_scc1 .Ltrp1_i10_s5
	s_sub_u32 s26, s26, 0x200
	s_branch .Ltrp1_i10_s6

.Ltrp1_i10_c:
	s_lshl_b32 s4, s24, 6
	s_mul_i32 s4, s25, s4
	s_lshl_b32 s5, s27, 7
	s_add_u32 s4, s4, s5
	s_add_u32 s10, s22, s4
	s_addc_u32 s11, s23, 0
	v_mad_u32_u24 v6, v1, s24, v2
	s_lshl_b32 s4, s29, 5
	s_mul_i32 s4, s27, s4
	s_lshl_b32 s5, s25, 7
	s_add_u32 s4, s4, s5
	s_add_u32 s4, s4, s28
	s_add_u32 s82, s72, s4
	s_addc_u32 s83, s73, 0
	s_mov_b32 s84, s29
	s_mov_b32 s85, s31
	s_lshl_b32 s4, s25, 8
	s_add_u32 s4, s4, s30
	s_add_u32 s12, s70, s4
	s_addc_u32 s13, s71, 0
	s_lshl_b32 s14, s24, 3
	global_load_dwordx4 v[124:127], v6, s[10:11]
	s_add_u32 s10, s10, s14
	s_addc_u32 s11, s11, 0
	global_load_dwordx4 v[128:131], v6, s[10:11]
	s_add_u32 s10, s10, s14
	s_addc_u32 s11, s11, 0
	global_load_dwordx4 v[132:135], v6, s[10:11]
	s_add_u32 s10, s10, s14
	s_addc_u32 s11, s11, 0
	global_load_dwordx4 v[136:139], v6, s[10:11]
	s_add_u32 s10, s10, s14
	s_addc_u32 s11, s11, 0
	global_load_dwordx4 v[140:143], v6, s[10:11]
	s_add_u32 s10, s10, s14
	s_addc_u32 s11, s11, 0
	global_load_dwordx4 v[144:147], v6, s[10:11]
	s_add_u32 s10, s10, s14
	s_addc_u32 s11, s11, 0
	global_load_dwordx4 v[148:151], v6, s[10:11]
	s_add_u32 s10, s10, s14
	s_addc_u32 s11, s11, 0
	global_load_dwordx4 v[152:155], v6, s[10:11]
	global_load_dwordx4 v[156:159], v5, s[12:13]
	global_load_dwordx4 v[160:163], v5, s[12:13] offset:16
	s_add_u32 s20, s20, s21
	s_add_u32 s42, s42, 1

.Ltrp1_go_3:
	ds_write2_b32 v207, v164, v165 offset1:1
	ds_write2_b32 v207, v166, v167 offset0:2 offset1:3
	ds_write2_b32 v208, v168, v169 offset1:1
	ds_write2_b32 v208, v170, v171 offset0:2 offset1:3
	ds_write2_b32 v209, v172, v173 offset1:1
	ds_write2_b32 v209, v174, v175 offset0:2 offset1:3
	ds_write2_b32 v210, v176, v177 offset1:1
	ds_write2_b32 v210, v178, v179 offset0:2 offset1:3
	ds_write2_b32 v211, v180, v181 offset1:1
	ds_write2_b32 v211, v182, v183 offset0:2 offset1:3
	ds_write2_b32 v212, v184, v185 offset1:1
	ds_write2_b32 v212, v186, v187 offset0:2 offset1:3
	ds_write2_b32 v213, v188, v189 offset1:1
	ds_write2_b32 v213, v190, v191 offset0:2 offset1:3
	ds_write2_b32 v214, v192, v193 offset1:1
	ds_write2_b32 v214, v194, v195 offset0:2 offset1:3
	v_mad_u32_u24 v8, v1, s88, v2
	s_lshl_b32 s4, s88, 3
	s_nop 0
	v_add_u32_e32 v9, s4, v8
	v_add_u32_e32 v10, s4, v9
	v_add_u32_e32 v11, s4, v10
	s_waitcnt lgkmcnt(0)
	ds_read2_b32 v[12:13], v4 offset1:33
	ds_read2_b32 v[14:15], v4 offset0:66 offset1:99
	ds_read2_b32 v[16:17], v4 offset0:132 offset1:165
	ds_read2_b32 v[18:19], v4 offset0:198 offset1:231
	ds_read2_b32 v[20:21], v4 offset0:8 offset1:41
	ds_read2_b32 v[22:23], v4 offset0:74 offset1:107
	ds_read2_b32 v[24:25], v4 offset0:140 offset1:173
	ds_read2_b32 v[26:27], v4 offset0:206 offset1:239
	ds_read2_b32 v[28:29], v4 offset0:16 offset1:49
	ds_read2_b32 v[30:31], v4 offset0:82 offset1:115
	ds_read2_b32 v[32:33], v4 offset0:148 offset1:181
	ds_read2_b32 v[34:35], v4 offset0:214 offset1:247
	ds_read2_b32 v[36:37], v4 offset0:24 offset1:57
	ds_read2_b32 v[38:39], v4 offset0:90 offset1:123
	ds_read2_b32 v[40:41], v4 offset0:156 offset1:189
	ds_read2_b32 v[42:43], v4 offset0:222 offset1:255
	s_cmp_eq_u32 s90, 0
	s_waitcnt lgkmcnt(0)
	s_cbranch_scc1 .Ltrp1_p11_ng
	v_mul_f32_e32 v12, v196, v12
	v_mul_f32_e32 v13, v197, v13
	v_mul_f32_e32 v14, v198, v14
	v_mul_f32_e32 v15, v199, v15
	v_mul_f32_e32 v16, v200, v16
	v_mul_f32_e32 v17, v201, v17
	v_mul_f32_e32 v18, v202, v18
	v_mul_f32_e32 v19, v203, v19
	v_mul_f32_e32 v20, v196, v20
	v_mul_f32_e32 v21, v197, v21
	v_mul_f32_e32 v22, v198, v22
	v_mul_f32_e32 v23, v199, v23
	v_mul_f32_e32 v24, v200, v24
	v_mul_f32_e32 v25, v201, v25
	v_mul_f32_e32 v26, v202, v26
	v_mul_f32_e32 v27, v203, v27
	v_mul_f32_e32 v28, v196, v28
	v_mul_f32_e32 v29, v197, v29
	v_mul_f32_e32 v30, v198, v30
	v_mul_f32_e32 v31, v199, v31
	v_mul_f32_e32 v32, v200, v32
	v_mul_f32_e32 v33, v201, v33
	v_mul_f32_e32 v34, v202, v34
	v_mul_f32_e32 v35, v203, v35
	v_mul_f32_e32 v36, v196, v36
	v_mul_f32_e32 v37, v197, v37
	v_mul_f32_e32 v38, v198, v38
	v_mul_f32_e32 v39, v199, v39
	v_mul_f32_e32 v40, v200, v40
	v_mul_f32_e32 v41, v201, v41
	v_mul_f32_e32 v42, v202, v42
	v_mul_f32_e32 v43, v203, v43
.Ltrp1_p11_ng:
	v_cvt_pk_bf16_f32 v12, v12, v13
	v_cvt_pk_bf16_f32 v13, v14, v15
	v_cvt_pk_bf16_f32 v14, v16, v17
	v_cvt_pk_bf16_f32 v15, v18, v19
	v_cvt_pk_bf16_f32 v20, v20, v21
	v_cvt_pk_bf16_f32 v21, v22, v23
	v_cvt_pk_bf16_f32 v22, v24, v25
	v_cvt_pk_bf16_f32 v23, v26, v27
	v_cvt_pk_bf16_f32 v28, v28, v29
	v_cvt_pk_bf16_f32 v29, v30, v31
	v_cvt_pk_bf16_f32 v30, v32, v33
	v_cvt_pk_bf16_f32 v31, v34, v35
	v_cvt_pk_bf16_f32 v36, v36, v37
	v_cvt_pk_bf16_f32 v37, v38, v39
	v_cvt_pk_bf16_f32 v38, v40, v41
	v_cvt_pk_bf16_f32 v39, v42, v43
	global_store_dwordx4 v8, v[12:15], s[86:87]
	global_store_dwordx4 v9, v[20:23], s[86:87]
	global_store_dwordx4 v10, v[28:31], s[86:87]
	global_store_dwordx4 v11, v[36:39], s[86:87]
	s_sub_u32 s42, s42, 1
	s_add_u32 s43, s43, 1
	s_cmp_ge_u32 s20, 0x1c98
	s_cbranch_scc1 .Ltrp1_ni_3
	s_mov_b32 s26, s20
	s_cmp_lt_u32 s26, 0x2c00
	s_cbranch_scc1 .Ltrp1_i12_s0
	s_sub_u32 s26, s26, 0x2c00
	s_cmp_lt_u32 s26, 0x1600
	s_cbranch_scc1 .Ltrp1_i12_s1
	s_sub_u32 s26, s26, 0x1600
	s_cmp_lt_u32 s26, 0x800
	s_cbranch_scc1 .Ltrp1_i12_s2
	s_sub_u32 s26, s26, 0x800
	s_cmp_lt_u32 s26, 0x400
	s_cbranch_scc1 .Ltrp1_i12_s3
	s_sub_u32 s26, s26, 0x400
	s_cmp_lt_u32 s26, 0x400
	s_cbranch_scc1 .Ltrp1_i12_s4
	s_sub_u32 s26, s26, 0x400
	s_cmp_lt_u32 s26, 0x200
	s_cbranch_scc1 .Ltrp1_i12_s5
	s_sub_u32 s26, s26, 0x200
	s_branch .Ltrp1_i12_s6

.Ltrp1_ni_3:
	s_cmp_eq_u32 s42, 0
	s_cbranch_scc1 .Lrc_p1skip
	s_branch .Ltrp1_st0

.LBB0_689:
	s_add_i32 s16, s28, s34
	s_ashr_i32 s17, s16, 31
	v_lshl_add_u64 v[2:3], v[30:31], 0, s[16:17]
	v_lshlrev_b64 v[2:3], 9, v[2:3]
	v_lshl_add_u64 v[14:15], v[18:19], 0, v[2:3]
	global_load_dwordx4 v[2:5], v[14:15], off
	global_load_dwordx4 v[6:9], v[14:15], off offset:64
	global_load_dwordx4 v[140:143], v[14:15], off offset:128
	global_load_dwordx4 v[144:147], v[14:15], off offset:192
	global_load_dwordx4 v[148:151], v[14:15], off offset:256
	global_load_dwordx4 v[152:155], v[14:15], off offset:320
	global_load_dwordx4 v[156:159], v[14:15], off offset:384
	global_load_dwordx4 v[160:163], v[14:15], off offset:448
	ds_read_b128 v[10:13], v37
	ds_read_b128 v[38:41], v37 offset:64
	ds_read_b128 v[42:45], v37 offset:8448
	ds_read_b128 v[46:49], v37 offset:8512
	ds_read_b128 v[50:53], v37 offset:16896
	ds_read_b128 v[54:57], v37 offset:16960
	ds_read_b128 v[58:61], v37 offset:25344
	ds_read_b128 v[62:65], v37 offset:25408
	s_or_b32 s0, s34, s29
	s_lshr_b32 s10, s0, 5
	s_lshl_b64 s[16:17], s[10:11], 13
	s_add_u32 s16, s30, s16
	s_addc_u32 s17, s31, s17
	s_mov_b64 s[18:19], -1
	s_and_b64 vcc, exec, s[14:15]
	s_waitcnt vmcnt(1) lgkmcnt(7)
	v_mfma_f32_16x16x32_bf16 v[10:13], v[10:13], v[2:5], 0
	s_waitcnt lgkmcnt(5)
	v_mfma_f32_16x16x32_bf16 v[42:45], v[42:45], v[2:5], 0
	s_waitcnt vmcnt(0)
	v_mfma_f32_16x16x32_bf16 v[10:13], v[38:41], v[6:9], v[10:13]
	s_waitcnt lgkmcnt(4)
	v_mfma_f32_16x16x32_bf16 v[38:41], v[46:49], v[6:9], v[42:45]
	s_nop 3
	global_load_dwordx4 v[42:45], v[14:15], off offset:128
	s_waitcnt lgkmcnt(3)
	v_mfma_f32_16x16x32_bf16 v[50:53], v[50:53], v[2:5], 0
	s_waitcnt lgkmcnt(1)
	v_mfma_f32_16x16x32_bf16 v[2:5], v[58:61], v[2:5], 0
	v_mfma_f32_16x16x32_bf16 v[46:49], v[54:57], v[6:9], v[50:53]
	s_nop 4
	global_load_dwordx4 v[50:53], v[14:15], off offset:192
	s_waitcnt lgkmcnt(0)
	v_mfma_f32_16x16x32_bf16 v[2:5], v[62:65], v[6:9], v[2:5]
	ds_read_b128 v[6:9], v37 offset:128
	ds_read_b128 v[54:57], v37 offset:192
	s_waitcnt vmcnt(1) lgkmcnt(1)
	v_mfma_f32_16x16x32_bf16 v[6:9], v[6:9], v[42:45], v[10:13]
	s_nop 2
	ds_read_b128 v[10:13], v37 offset:8576
	ds_read_b128 v[58:61], v37 offset:8640
	s_waitcnt lgkmcnt(1)
	v_mfma_f32_16x16x32_bf16 v[10:13], v[10:13], v[42:45], v[38:41]
	s_nop 2
	ds_read_b128 v[38:41], v37 offset:17024
	ds_read_b128 v[62:65], v37 offset:17088
	s_waitcnt lgkmcnt(1)
	v_mfma_f32_16x16x32_bf16 v[38:41], v[38:41], v[42:45], v[46:49]
	s_nop 2
	ds_read_b128 v[46:49], v37 offset:25472
	ds_read_b128 v[66:69], v37 offset:25536
	s_waitcnt lgkmcnt(1)
	v_mfma_f32_16x16x32_bf16 v[2:5], v[46:49], v[42:45], v[2:5]
	global_load_dwordx4 v[42:45], v[14:15], off offset:256
	global_load_dwordx4 v[46:49], v[14:15], off offset:320
	s_waitcnt vmcnt(2)
	v_mfma_f32_16x16x32_bf16 v[6:9], v[54:57], v[50:53], v[6:9]
	v_mfma_f32_16x16x32_bf16 v[10:13], v[58:61], v[50:53], v[10:13]
	v_mfma_f32_16x16x32_bf16 v[38:41], v[62:65], v[50:53], v[38:41]
	s_waitcnt lgkmcnt(0)
	v_mfma_f32_16x16x32_bf16 v[2:5], v[66:69], v[50:53], v[2:5]
	ds_read_b128 v[50:53], v37 offset:256
	ds_read_b128 v[54:57], v37 offset:320
	s_waitcnt vmcnt(1) lgkmcnt(1)
	v_mfma_f32_16x16x32_bf16 v[6:9], v[50:53], v[42:45], v[6:9]
	ds_read_b128 v[50:53], v37 offset:8704
	ds_read_b128 v[58:61], v37 offset:8768
	s_waitcnt lgkmcnt(1)
	v_mfma_f32_16x16x32_bf16 v[10:13], v[50:53], v[42:45], v[10:13]
	ds_read_b128 v[50:53], v37 offset:17152
	ds_read_b128 v[62:65], v37 offset:17216
	s_waitcnt lgkmcnt(1)
	v_mfma_f32_16x16x32_bf16 v[38:41], v[50:53], v[42:45], v[38:41]
	ds_read_b128 v[50:53], v37 offset:25600
	ds_read_b128 v[66:69], v37 offset:25664
	s_waitcnt lgkmcnt(1)
	v_mfma_f32_16x16x32_bf16 v[2:5], v[50:53], v[42:45], v[2:5]
	global_load_dwordx4 v[42:45], v[14:15], off offset:384
	global_load_dwordx4 v[50:53], v[14:15], off offset:448
	s_waitcnt vmcnt(2)
	v_mfma_f32_16x16x32_bf16 v[6:9], v[54:57], v[46:49], v[6:9]
	v_mfma_f32_16x16x32_bf16 v[10:13], v[58:61], v[46:49], v[10:13]
	v_mfma_f32_16x16x32_bf16 v[38:41], v[62:65], v[46:49], v[38:41]
	s_waitcnt lgkmcnt(0)
	v_mfma_f32_16x16x32_bf16 v[2:5], v[66:69], v[46:49], v[2:5]
	ds_read_b128 v[46:49], v37 offset:384
	ds_read_b128 v[54:57], v37 offset:448
	s_waitcnt vmcnt(1) lgkmcnt(1)
	v_mfma_f32_16x16x32_bf16 v[6:9], v[46:49], v[42:45], v[6:9]
	ds_read_b128 v[46:49], v37 offset:8832
	ds_read_b128 v[58:61], v37 offset:8896
	s_waitcnt lgkmcnt(1)
	v_mfma_f32_16x16x32_bf16 v[46:49], v[46:49], v[42:45], v[10:13]
	s_nop 2
	ds_read_b128 v[10:13], v37 offset:17280
	ds_read_b128 v[62:65], v37 offset:17344
	s_waitcnt lgkmcnt(1)
	v_mfma_f32_16x16x32_bf16 v[38:41], v[10:13], v[42:45], v[38:41]
	ds_read_b128 v[10:13], v37 offset:25728
	ds_read_b128 v[66:69], v37 offset:25792
	s_waitcnt lgkmcnt(1)
	v_mfma_f32_16x16x32_bf16 v[42:45], v[10:13], v[42:45], v[2:5]
	s_waitcnt vmcnt(0)
	v_mfma_f32_16x16x32_bf16 v[12:15], v[54:57], v[50:53], v[6:9]
	v_mfma_f32_16x16x32_bf16 v[8:11], v[58:61], v[50:53], v[46:49]
	v_mfma_f32_16x16x32_bf16 v[4:7], v[62:65], v[50:53], v[38:41]
	s_nop 5
	v_add_f32_e64 v32, v12, 0
	v_add_f32_e64 v33, v13, 0
	v_pk_add_f32 v[12:13], v[8:9], 0 op_sel_hi:[1,0]
	v_pk_add_f32 v[8:9], v[4:5], 0 op_sel_hi:[1,0]
	s_waitcnt lgkmcnt(0)
	v_mfma_f32_16x16x32_bf16 v[2:5], v[66:69], v[50:53], v[42:45]
	s_nop 7
	v_pk_add_f32 v[2:3], v[2:3], 0 op_sel_hi:[1,0]
	s_cbranch_vccz .LBB0_691
	v_and_or_b32 v21, s35, 4, v1
	v_lshlrev_b32_e32 v38, 1, v21
	v_mov_b32_e32 v39, v17
	v_lshl_add_u64 v[38:39], s[16:17], 0, v[38:39]
	v_mov_b32_e32 v21, v17
	v_pk_add_f32 v[40:41], v[14:15], 0 op_sel_hi:[1,0]
	v_lshl_add_u64 v[38:39], v[38:39], 0, v[20:21]
	v_cvt_pk_bf16_f32 v23, v32, v33
	v_cvt_pk_bf16_f32 v25, v40, v41
	v_lshl_add_u64 v[40:41], v[38:39], 0, s[12:13]
	v_add_co_u32_e32 v38, vcc, s26, v38
	s_mov_b64 s[18:19], 0
	s_nop 0
	v_addc_co_u32_e32 v39, vcc, 0, v39, vcc
	global_store_short v[38:39], v23, off
	global_store_short_d16_hi v[40:41], v23, off offset:16
	global_store_short v[40:41], v25, off offset:32
	global_store_short_d16_hi v[40:41], v25, off offset:48
	v_cvt_pk_bf16_f32 v21, v12, v13
	v_pk_add_f32 v[38:39], v[10:11], 0 op_sel_hi:[1,0]
	s_nop 0
	v_cvt_pk_bf16_f32 v23, v38, v39
	global_store_short v[40:41], v21, off offset:1024
	global_store_short_d16_hi v[40:41], v21, off offset:1040
	global_store_short v[40:41], v23, off offset:1056
	global_store_short_d16_hi v[40:41], v23, off offset:1072
	v_cvt_pk_bf16_f32 v21, v8, v9
	v_pk_add_f32 v[38:39], v[6:7], 0 op_sel_hi:[1,0]
	s_nop 0
	v_cvt_pk_bf16_f32 v23, v38, v39
	global_store_short v[40:41], v21, off offset:2048
	global_store_short_d16_hi v[40:41], v21, off offset:2064
	global_store_short v[40:41], v23, off offset:2080
	global_store_short_d16_hi v[40:41], v23, off offset:2096
	v_cvt_pk_bf16_f32 v21, v2, v3
	v_pk_add_f32 v[38:39], v[4:5], 0 op_sel_hi:[1,0]
	s_nop 0
	v_cvt_pk_bf16_f32 v23, v38, v39
	global_store_short v[40:41], v21, off offset:3072
	global_store_short_d16_hi v[40:41], v21, off offset:3088
	global_store_short v[40:41], v23, off offset:3104
	global_store_short_d16_hi v[40:41], v23, off offset:3120

.LBB0_693:
	s_cmp_lt_u32 s2, 8
	s_barrier
	s_cbranch_scc1 .LBB0_950
	s_mov_b64 exec, -1
	v_readlane_b32 s0, v254, 0
	v_readlane_b32 s1, v254, 1
	s_nop 4
	s_load_dwordx2 s[56:57], s[0:1], 0xa8
	s_load_dwordx2 s[58:59], s[0:1], 0xc0
	s_load_dwordx2 s[60:61], s[0:1], 0x88
	s_load_dwordx2 s[62:63], s[0:1], 0x78
	s_load_dwordx2 s[64:65], s[0:1], 0x80
	s_load_dwordx2 s[66:67], s[0:1], 0x90
	s_load_dwordx2 s[68:69], s[0:1], 0xa0
	s_load_dwordx2 s[70:71], s[0:1], 0x48
	s_load_dwordx2 s[72:73], s[0:1], 0xd8
	s_load_dword s3, s[0:1], 0xe8
	v_readfirstlane_b32 s4, v0
	v_and_b32_e32 v7, 63, v0
	s_lshr_b32 s4, s4, 6
	v_lshrrev_b32_e32 v1, 3, v7
	v_and_b32_e32 v2, 7, v7
	s_lshl_b32 s5, s4, 14
	v_lshlrev_b32_e32 v5, 5, v2
	s_movk_i32 s14, 0x420
	v_mul_u32_u24_e32 v4, s14, v2
	v_lshlrev_b32_e32 v2, 4, v2
	s_movk_i32 s14, 0x84
	v_mad_u32_u24 v3, v1, s14, v2
	v_lshl_add_u32 v4, v1, 2, v4
	v_add_u32_e32 v3, s5, v3
	v_add_u32_e32 v4, s5, v4
	v_mov_b32_e32 v207, v3
	v_add_u32_e32 v208, 1056, v3
	v_add_u32_e32 v209, 2112, v3
	v_add_u32_e32 v210, 3168, v3
	v_add_u32_e32 v211, 4224, v3
	v_add_u32_e32 v212, 5280, v3
	v_add_u32_e32 v213, 6336, v3
	v_add_u32_e32 v214, 7392, v3
	s_waitcnt lgkmcnt(0)
	s_sub_u32 s5, s2, 8
	s_lshl_b32 s5, s5, 3
	s_add_u32 s20, s5, s4
	s_sub_u32 s21, s3, 8
	s_lshl_b32 s21, s21, 3
	s_add_u32 s20, s20, 0x1c98
	s_cmp_ge_u32 s20, 0x5600
	s_cbranch_scc1 .Lrc_p3call
	s_mov_b32 s42, 0
	s_mov_b32 s43, 0
	s_mov_b32 s26, s20
	s_cmp_lt_u32 s26, 0x2c00
	s_cbranch_scc1 .Ltrp3_i1_s0
	s_sub_u32 s26, s26, 0x2c00
	s_cmp_lt_u32 s26, 0x1600
	s_cbranch_scc1 .Ltrp3_i1_s1
	s_sub_u32 s26, s26, 0x1600
	s_cmp_lt_u32 s26, 0x800
	s_cbranch_scc1 .Ltrp3_i1_s2
	s_sub_u32 s26, s26, 0x800
	s_cmp_lt_u32 s26, 0x400
	s_cbranch_scc1 .Ltrp3_i1_s3
	s_sub_u32 s26, s26, 0x400
	s_cmp_lt_u32 s26, 0x400
	s_cbranch_scc1 .Ltrp3_i1_s4
	s_sub_u32 s26, s26, 0x400
	s_cmp_lt_u32 s26, 0x200
	s_cbranch_scc1 .Ltrp3_i1_s5
	s_sub_u32 s26, s26, 0x200
	s_branch .Ltrp3_i1_s6

.Ltrp3_i1_c:
	s_lshl_b32 s4, s24, 6
	s_mul_i32 s4, s25, s4
	s_lshl_b32 s5, s27, 7
	s_add_u32 s4, s4, s5
	s_add_u32 s10, s22, s4
	s_addc_u32 s11, s23, 0
	v_mad_u32_u24 v6, v1, s24, v2
	s_lshl_b32 s4, s29, 5
	s_mul_i32 s4, s27, s4
	s_lshl_b32 s5, s25, 7
	s_add_u32 s4, s4, s5
	s_add_u32 s4, s4, s28
	s_add_u32 s74, s72, s4
	s_addc_u32 s75, s73, 0
	s_mov_b32 s76, s29
	s_mov_b32 s77, s31
	s_lshl_b32 s4, s25, 8
	s_add_u32 s4, s4, s30
	s_add_u32 s12, s70, s4
	s_addc_u32 s13, s71, 0
	s_lshl_b32 s14, s24, 3
	global_load_dwordx4 v[44:47], v6, s[10:11]
	s_add_u32 s10, s10, s14
	s_addc_u32 s11, s11, 0
	global_load_dwordx4 v[48:51], v6, s[10:11]
	s_add_u32 s10, s10, s14
	s_addc_u32 s11, s11, 0
	global_load_dwordx4 v[52:55], v6, s[10:11]
	s_add_u32 s10, s10, s14
	s_addc_u32 s11, s11, 0
	global_load_dwordx4 v[56:59], v6, s[10:11]
	s_add_u32 s10, s10, s14
	s_addc_u32 s11, s11, 0
	global_load_dwordx4 v[60:63], v6, s[10:11]
	s_add_u32 s10, s10, s14
	s_addc_u32 s11, s11, 0
	global_load_dwordx4 v[64:67], v6, s[10:11]
	s_add_u32 s10, s10, s14
	s_addc_u32 s11, s11, 0
	global_load_dwordx4 v[68:71], v6, s[10:11]
	s_add_u32 s10, s10, s14
	s_addc_u32 s11, s11, 0
	global_load_dwordx4 v[72:75], v6, s[10:11]
	global_load_dwordx4 v[76:79], v5, s[12:13]
	global_load_dwordx4 v[80:83], v5, s[12:13] offset:16
	s_add_u32 s20, s20, s21
	s_add_u32 s42, s42, 1
	s_cmp_ge_u32 s20, 0x5600
	s_cbranch_scc1 .Ltrp3_st0
	s_mov_b32 s26, s20
	s_cmp_lt_u32 s26, 0x2c00
	s_cbranch_scc1 .Ltrp3_i2_s0
	s_sub_u32 s26, s26, 0x2c00
	s_cmp_lt_u32 s26, 0x1600
	s_cbranch_scc1 .Ltrp3_i2_s1
	s_sub_u32 s26, s26, 0x1600
	s_cmp_lt_u32 s26, 0x800
	s_cbranch_scc1 .Ltrp3_i2_s2
	s_sub_u32 s26, s26, 0x800
	s_cmp_lt_u32 s26, 0x400
	s_cbranch_scc1 .Ltrp3_i2_s3
	s_sub_u32 s26, s26, 0x400
	s_cmp_lt_u32 s26, 0x400
	s_cbranch_scc1 .Ltrp3_i2_s4
	s_sub_u32 s26, s26, 0x400
	s_cmp_lt_u32 s26, 0x200
	s_cbranch_scc1 .Ltrp3_i2_s5
	s_sub_u32 s26, s26, 0x200
	s_branch .Ltrp3_i2_s6

.Ltrp3_i2_c:
	s_lshl_b32 s4, s24, 6
	s_mul_i32 s4, s25, s4
	s_lshl_b32 s5, s27, 7
	s_add_u32 s4, s4, s5
	s_add_u32 s10, s22, s4
	s_addc_u32 s11, s23, 0
	v_mad_u32_u24 v6, v1, s24, v2
	s_lshl_b32 s4, s29, 5
	s_mul_i32 s4, s27, s4
	s_lshl_b32 s5, s25, 7
	s_add_u32 s4, s4, s5
	s_add_u32 s4, s4, s28
	s_add_u32 s78, s72, s4
	s_addc_u32 s79, s73, 0
	s_mov_b32 s80, s29
	s_mov_b32 s81, s31
	s_lshl_b32 s4, s25, 8
	s_add_u32 s4, s4, s30
	s_add_u32 s12, s70, s4
	s_addc_u32 s13, s71, 0
	s_lshl_b32 s14, s24, 3
	global_load_dwordx4 v[84:87], v6, s[10:11]
	s_add_u32 s10, s10, s14
	s_addc_u32 s11, s11, 0
	global_load_dwordx4 v[88:91], v6, s[10:11]
	s_add_u32 s10, s10, s14
	s_addc_u32 s11, s11, 0
	global_load_dwordx4 v[92:95], v6, s[10:11]
	s_add_u32 s10, s10, s14
	s_addc_u32 s11, s11, 0
	global_load_dwordx4 v[96:99], v6, s[10:11]
	s_add_u32 s10, s10, s14
	s_addc_u32 s11, s11, 0
	global_load_dwordx4 v[100:103], v6, s[10:11]
	s_add_u32 s10, s10, s14
	s_addc_u32 s11, s11, 0
	global_load_dwordx4 v[104:107], v6, s[10:11]
	s_add_u32 s10, s10, s14
	s_addc_u32 s11, s11, 0
	global_load_dwordx4 v[108:111], v6, s[10:11]
	s_add_u32 s10, s10, s14
	s_addc_u32 s11, s11, 0
	global_load_dwordx4 v[112:115], v6, s[10:11]
	global_load_dwordx4 v[116:119], v5, s[12:13]
	global_load_dwordx4 v[120:123], v5, s[12:13] offset:16
	s_add_u32 s20, s20, s21
	s_add_u32 s42, s42, 1
	s_cmp_ge_u32 s20, 0x5600
	s_cbranch_scc1 .Ltrp3_st0
	s_mov_b32 s26, s20
	s_cmp_lt_u32 s26, 0x2c00
	s_cbranch_scc1 .Ltrp3_i3_s0
	s_sub_u32 s26, s26, 0x2c00
	s_cmp_lt_u32 s26, 0x1600
	s_cbranch_scc1 .Ltrp3_i3_s1
	s_sub_u32 s26, s26, 0x1600
	s_cmp_lt_u32 s26, 0x800
	s_cbranch_scc1 .Ltrp3_i3_s2
	s_sub_u32 s26, s26, 0x800
	s_cmp_lt_u32 s26, 0x400
	s_cbranch_scc1 .Ltrp3_i3_s3
	s_sub_u32 s26, s26, 0x400
	s_cmp_lt_u32 s26, 0x400
	s_cbranch_scc1 .Ltrp3_i3_s4
	s_sub_u32 s26, s26, 0x400
	s_cmp_lt_u32 s26, 0x200
	s_cbranch_scc1 .Ltrp3_i3_s5
	s_sub_u32 s26, s26, 0x200
	s_branch .Ltrp3_i3_s6

.Ltrp3_i3_c:
	s_lshl_b32 s4, s24, 6
	s_mul_i32 s4, s25, s4
	s_lshl_b32 s5, s27, 7
	s_add_u32 s4, s4, s5
	s_add_u32 s10, s22, s4
	s_addc_u32 s11, s23, 0
	v_mad_u32_u24 v6, v1, s24, v2
	s_lshl_b32 s4, s29, 5
	s_mul_i32 s4, s27, s4
	s_lshl_b32 s5, s25, 7
	s_add_u32 s4, s4, s5
	s_add_u32 s4, s4, s28
	s_add_u32 s82, s72, s4
	s_addc_u32 s83, s73, 0
	s_mov_b32 s84, s29
	s_mov_b32 s85, s31
	s_lshl_b32 s4, s25, 8
	s_add_u32 s4, s4, s30
	s_add_u32 s12, s70, s4
	s_addc_u32 s13, s71, 0
	s_lshl_b32 s14, s24, 3
	global_load_dwordx4 v[124:127], v6, s[10:11]
	s_add_u32 s10, s10, s14
	s_addc_u32 s11, s11, 0
	global_load_dwordx4 v[128:131], v6, s[10:11]
	s_add_u32 s10, s10, s14
	s_addc_u32 s11, s11, 0
	global_load_dwordx4 v[132:135], v6, s[10:11]
	s_add_u32 s10, s10, s14
	s_addc_u32 s11, s11, 0
	global_load_dwordx4 v[136:139], v6, s[10:11]
	s_add_u32 s10, s10, s14
	s_addc_u32 s11, s11, 0
	global_load_dwordx4 v[140:143], v6, s[10:11]
	s_add_u32 s10, s10, s14
	s_addc_u32 s11, s11, 0
	global_load_dwordx4 v[144:147], v6, s[10:11]
	s_add_u32 s10, s10, s14
	s_addc_u32 s11, s11, 0
	global_load_dwordx4 v[148:151], v6, s[10:11]
	s_add_u32 s10, s10, s14
	s_addc_u32 s11, s11, 0
	global_load_dwordx4 v[152:155], v6, s[10:11]
	global_load_dwordx4 v[156:159], v5, s[12:13]
	global_load_dwordx4 v[160:163], v5, s[12:13] offset:16
	s_add_u32 s20, s20, s21
	s_add_u32 s42, s42, 1
	s_cmp_ge_u32 s20, 0x5600
	s_cbranch_scc1 .Ltrp3_st0
	s_mov_b32 s26, s20
	s_cmp_lt_u32 s26, 0x2c00
	s_cbranch_scc1 .Ltrp3_i4_s0
	s_sub_u32 s26, s26, 0x2c00
	s_cmp_lt_u32 s26, 0x1600
	s_cbranch_scc1 .Ltrp3_i4_s1
	s_sub_u32 s26, s26, 0x1600
	s_cmp_lt_u32 s26, 0x800
	s_cbranch_scc1 .Ltrp3_i4_s2
	s_sub_u32 s26, s26, 0x800
	s_cmp_lt_u32 s26, 0x400
	s_cbranch_scc1 .Ltrp3_i4_s3
	s_sub_u32 s26, s26, 0x400
	s_cmp_lt_u32 s26, 0x400
	s_cbranch_scc1 .Ltrp3_i4_s4
	s_sub_u32 s26, s26, 0x400
	s_cmp_lt_u32 s26, 0x200
	s_cbranch_scc1 .Ltrp3_i4_s5
	s_sub_u32 s26, s26, 0x200
	s_branch .Ltrp3_i4_s6

.Ltrp3_p5_ng:
	v_cvt_pk_bf16_f32 v12, v12, v13
	v_cvt_pk_bf16_f32 v13, v14, v15
	v_cvt_pk_bf16_f32 v14, v16, v17
	v_cvt_pk_bf16_f32 v15, v18, v19
	v_cvt_pk_bf16_f32 v20, v20, v21
	v_cvt_pk_bf16_f32 v21, v22, v23
	v_cvt_pk_bf16_f32 v22, v24, v25
	v_cvt_pk_bf16_f32 v23, v26, v27
	v_cvt_pk_bf16_f32 v28, v28, v29
	v_cvt_pk_bf16_f32 v29, v30, v31
	v_cvt_pk_bf16_f32 v30, v32, v33
	v_cvt_pk_bf16_f32 v31, v34, v35
	v_cvt_pk_bf16_f32 v36, v36, v37
	v_cvt_pk_bf16_f32 v37, v38, v39
	v_cvt_pk_bf16_f32 v38, v40, v41
	v_cvt_pk_bf16_f32 v39, v42, v43
	global_store_dwordx4 v8, v[12:15], s[74:75]
	global_store_dwordx4 v9, v[20:23], s[74:75]
	global_store_dwordx4 v10, v[28:31], s[74:75]
	global_store_dwordx4 v11, v[36:39], s[74:75]
	s_sub_u32 s42, s42, 1
	s_add_u32 s43, s43, 1
	s_cmp_ge_u32 s20, 0x5600
	s_cbranch_scc1 .Ltrp3_ni_0
	s_mov_b32 s26, s20
	s_cmp_lt_u32 s26, 0x2c00
	s_cbranch_scc1 .Ltrp3_i6_s0
	s_sub_u32 s26, s26, 0x2c00
	s_cmp_lt_u32 s26, 0x1600
	s_cbranch_scc1 .Ltrp3_i6_s1
	s_sub_u32 s26, s26, 0x1600
	s_cmp_lt_u32 s26, 0x800
	s_cbranch_scc1 .Ltrp3_i6_s2
	s_sub_u32 s26, s26, 0x800
	s_cmp_lt_u32 s26, 0x400
	s_cbranch_scc1 .Ltrp3_i6_s3
	s_sub_u32 s26, s26, 0x400
	s_cmp_lt_u32 s26, 0x400
	s_cbranch_scc1 .Ltrp3_i6_s4
	s_sub_u32 s26, s26, 0x400
	s_cmp_lt_u32 s26, 0x200
	s_cbranch_scc1 .Ltrp3_i6_s5
	s_sub_u32 s26, s26, 0x200
	s_branch .Ltrp3_i6_s6

.Ltrp3_p7_ng:
	v_cvt_pk_bf16_f32 v12, v12, v13
	v_cvt_pk_bf16_f32 v13, v14, v15
	v_cvt_pk_bf16_f32 v14, v16, v17
	v_cvt_pk_bf16_f32 v15, v18, v19
	v_cvt_pk_bf16_f32 v20, v20, v21
	v_cvt_pk_bf16_f32 v21, v22, v23
	v_cvt_pk_bf16_f32 v22, v24, v25
	v_cvt_pk_bf16_f32 v23, v26, v27
	v_cvt_pk_bf16_f32 v28, v28, v29
	v_cvt_pk_bf16_f32 v29, v30, v31
	v_cvt_pk_bf16_f32 v30, v32, v33
	v_cvt_pk_bf16_f32 v31, v34, v35
	v_cvt_pk_bf16_f32 v36, v36, v37
	v_cvt_pk_bf16_f32 v37, v38, v39
	v_cvt_pk_bf16_f32 v38, v40, v41
	v_cvt_pk_bf16_f32 v39, v42, v43
	global_store_dwordx4 v8, v[12:15], s[78:79]
	global_store_dwordx4 v9, v[20:23], s[78:79]
	global_store_dwordx4 v10, v[28:31], s[78:79]
	global_store_dwordx4 v11, v[36:39], s[78:79]
	s_sub_u32 s42, s42, 1
	s_add_u32 s43, s43, 1
	s_cmp_ge_u32 s20, 0x5600
	s_cbranch_scc1 .Ltrp3_ni_1
	s_mov_b32 s26, s20
	s_cmp_lt_u32 s26, 0x2c00
	s_cbranch_scc1 .Ltrp3_i8_s0
	s_sub_u32 s26, s26, 0x2c00
	s_cmp_lt_u32 s26, 0x1600
	s_cbranch_scc1 .Ltrp3_i8_s1
	s_sub_u32 s26, s26, 0x1600
	s_cmp_lt_u32 s26, 0x800
	s_cbranch_scc1 .Ltrp3_i8_s2
	s_sub_u32 s26, s26, 0x800
	s_cmp_lt_u32 s26, 0x400
	s_cbranch_scc1 .Ltrp3_i8_s3
	s_sub_u32 s26, s26, 0x400
	s_cmp_lt_u32 s26, 0x400
	s_cbranch_scc1 .Ltrp3_i8_s4
	s_sub_u32 s26, s26, 0x400
	s_cmp_lt_u32 s26, 0x200
	s_cbranch_scc1 .Ltrp3_i8_s5
	s_sub_u32 s26, s26, 0x200
	s_branch .Ltrp3_i8_s6

.Ltrp3_p9_ng:
	v_cvt_pk_bf16_f32 v12, v12, v13
	v_cvt_pk_bf16_f32 v13, v14, v15
	v_cvt_pk_bf16_f32 v14, v16, v17
	v_cvt_pk_bf16_f32 v15, v18, v19
	v_cvt_pk_bf16_f32 v20, v20, v21
	v_cvt_pk_bf16_f32 v21, v22, v23
	v_cvt_pk_bf16_f32 v22, v24, v25
	v_cvt_pk_bf16_f32 v23, v26, v27
	v_cvt_pk_bf16_f32 v28, v28, v29
	v_cvt_pk_bf16_f32 v29, v30, v31
	v_cvt_pk_bf16_f32 v30, v32, v33
	v_cvt_pk_bf16_f32 v31, v34, v35
	v_cvt_pk_bf16_f32 v36, v36, v37
	v_cvt_pk_bf16_f32 v37, v38, v39
	v_cvt_pk_bf16_f32 v38, v40, v41
	v_cvt_pk_bf16_f32 v39, v42, v43
	global_store_dwordx4 v8, v[12:15], s[82:83]
	global_store_dwordx4 v9, v[20:23], s[82:83]
	global_store_dwordx4 v10, v[28:31], s[82:83]
	global_store_dwordx4 v11, v[36:39], s[82:83]
	s_sub_u32 s42, s42, 1
	s_add_u32 s43, s43, 1
	s_cmp_ge_u32 s20, 0x5600
	s_cbranch_scc1 .Ltrp3_ni_2
	s_mov_b32 s26, s20
	s_cmp_lt_u32 s26, 0x2c00
	s_cbranch_scc1 .Ltrp3_i10_s0
	s_sub_u32 s26, s26, 0x2c00
	s_cmp_lt_u32 s26, 0x1600
	s_cbranch_scc1 .Ltrp3_i10_s1
	s_sub_u32 s26, s26, 0x1600
	s_cmp_lt_u32 s26, 0x800
	s_cbranch_scc1 .Ltrp3_i10_s2
	s_sub_u32 s26, s26, 0x800
	s_cmp_lt_u32 s26, 0x400
	s_cbranch_scc1 .Ltrp3_i10_s3
	s_sub_u32 s26, s26, 0x400
	s_cmp_lt_u32 s26, 0x400
	s_cbranch_scc1 .Ltrp3_i10_s4
	s_sub_u32 s26, s26, 0x400
	s_cmp_lt_u32 s26, 0x200
	s_cbranch_scc1 .Ltrp3_i10_s5
	s_sub_u32 s26, s26, 0x200
	s_branch .Ltrp3_i10_s6

.Ltrp3_p11_ng:
	v_cvt_pk_bf16_f32 v12, v12, v13
	v_cvt_pk_bf16_f32 v13, v14, v15
	v_cvt_pk_bf16_f32 v14, v16, v17
	v_cvt_pk_bf16_f32 v15, v18, v19
	v_cvt_pk_bf16_f32 v20, v20, v21
	v_cvt_pk_bf16_f32 v21, v22, v23
	v_cvt_pk_bf16_f32 v22, v24, v25
	v_cvt_pk_bf16_f32 v23, v26, v27
	v_cvt_pk_bf16_f32 v28, v28, v29
	v_cvt_pk_bf16_f32 v29, v30, v31
	v_cvt_pk_bf16_f32 v30, v32, v33
	v_cvt_pk_bf16_f32 v31, v34, v35
	v_cvt_pk_bf16_f32 v36, v36, v37
	v_cvt_pk_bf16_f32 v37, v38, v39
	v_cvt_pk_bf16_f32 v38, v40, v41
	v_cvt_pk_bf16_f32 v39, v42, v43
	global_store_dwordx4 v8, v[12:15], s[86:87]
	global_store_dwordx4 v9, v[20:23], s[86:87]
	global_store_dwordx4 v10, v[28:31], s[86:87]
	global_store_dwordx4 v11, v[36:39], s[86:87]
	s_sub_u32 s42, s42, 1
	s_add_u32 s43, s43, 1
	s_cmp_ge_u32 s20, 0x5600
	s_cbranch_scc1 .Ltrp3_ni_3
	s_mov_b32 s26, s20
	s_cmp_lt_u32 s26, 0x2c00
	s_cbranch_scc1 .Ltrp3_i12_s0
	s_sub_u32 s26, s26, 0x2c00
	s_cmp_lt_u32 s26, 0x1600
	s_cbranch_scc1 .Ltrp3_i12_s1
	s_sub_u32 s26, s26, 0x1600
	s_cmp_lt_u32 s26, 0x800
	s_cbranch_scc1 .Ltrp3_i12_s2
	s_sub_u32 s26, s26, 0x800
	s_cmp_lt_u32 s26, 0x400
	s_cbranch_scc1 .Ltrp3_i12_s3
	s_sub_u32 s26, s26, 0x400
	s_cmp_lt_u32 s26, 0x400
	s_cbranch_scc1 .Ltrp3_i12_s4
	s_sub_u32 s26, s26, 0x400
	s_cmp_lt_u32 s26, 0x200
	s_cbranch_scc1 .Ltrp3_i12_s5
	s_sub_u32 s26, s26, 0x200
	s_branch .Ltrp3_i12_s6
